# P0 row-load hoist + tail_fixup partial loads issued together + final RMSNorm: gains preloaded, row loads issued together; on the micro-edit bundle
# speedup vs baseline: 1.0112x; 1.0047x over previous
.LBB0_638:
	s_ashr_i32 s6, s16, 3
	s_add_i32 s4, s6, 0x2000
	s_ashr_i32 s5, s4, 31
	s_lshl_b64 s[38:39], s[4:5], 12
	v_lshl_add_u64 v[16:17], v[2:3], 0, s[38:39]
	s_waitcnt lgkmcnt(0)
	global_load_dwordx2 v[192:193], v[16:17], off
	s_ashr_i32 s7, s6, 31
	s_lshl_b64 s[6:7], s[6:7], 10
	v_lshl_add_u64 v[22:23], v[4:5], 0, s[6:7]
	global_load_dwordx4 v[218:221], v[22:23], off
	v_add_co_u32_e64 v194, s[38:39], s22, v22
	s_nop 1
	v_addc_co_u32_e64 v195, s[38:39], 0, v23, s[38:39]
	global_load_dwordx4 v[222:225], v[194:195], off
	v_add_co_u32_e64 v194, s[38:39], s24, v22
	s_nop 1
	v_addc_co_u32_e64 v195, s[38:39], 0, v23, s[38:39]
	global_load_dwordx4 v[226:229], v[194:195], off
	v_add_co_u32_e64 v194, s[38:39], s25, v22
	s_nop 1
	v_addc_co_u32_e64 v195, s[38:39], 0, v23, s[38:39]
	global_load_dwordx4 v[230:233], v[194:195], off
	s_waitcnt vmcnt(0)
	v_lshlrev_b32_e32 v18, 16, v192
	v_and_b32_e32 v19, 0xffff0000, v192
	v_lshlrev_b32_e32 v20, 16, v193
	v_and_b32_e32 v21, 0xffff0000, v193
	v_pk_add_f32 v[18:19], v[218:219], v[18:19]
	v_pk_add_f32 v[20:21], v[220:221], v[20:21]
	v_pk_add_f32 v[18:19], v[222:223], v[18:19]
	v_pk_add_f32 v[20:21], v[224:225], v[20:21]
	v_pk_add_f32 v[18:19], v[226:227], v[18:19]
	v_pk_add_f32 v[20:21], v[228:229], v[20:21]
	v_pk_add_f32 v[14:15], v[232:233], v[20:21]
	v_pk_add_f32 v[12:13], v[230:231], v[18:19]
	v_mul_f32_e32 v18, v15, v15
	v_mul_f32_e32 v11, v13, v13
	v_fmac_f32_e32 v11, v12, v12
	v_fmac_f32_e32 v18, v14, v14
	v_add_f32_e32 v11, v11, v18
	v_bfe_u32 v18, v12, 16, 1
	v_add3_u32 v12, v12, v18, s23
	v_bfe_u32 v18, v13, 16, 1
	v_lshrrev_b32_e32 v12, 16, v12
	v_add3_u32 v13, v13, v18, s23
	v_and_or_b32 v12, v13, s83, v12
	v_bfe_u32 v13, v14, 16, 1
	v_add3_u32 v13, v14, v13, s23
	v_bfe_u32 v14, v15, 16, 1
	v_lshrrev_b32_e32 v13, 16, v13
	v_add3_u32 v14, v15, v14, s23
	v_and_or_b32 v13, v14, s83, v13
	global_store_dwordx2 v[16:17], v[12:13], off
	ds_bpermute_b32 v12, v1, v11
	s_waitcnt lgkmcnt(0)
	v_add_f32_e32 v11, v11, v12
	ds_bpermute_b32 v12, v6, v11
	s_waitcnt lgkmcnt(0)
	v_add_f32_e32 v11, v11, v12
	ds_bpermute_b32 v12, v7, v11
	s_waitcnt lgkmcnt(0)
	v_add_f32_e32 v11, v11, v12
	ds_bpermute_b32 v12, v8, v11
	s_waitcnt lgkmcnt(0)
	v_add_f32_e32 v11, v11, v12
	ds_bpermute_b32 v12, v9, v11
	s_waitcnt lgkmcnt(0)
	v_add_f32_e32 v11, v11, v12
	ds_bpermute_b32 v12, v10, v11
	s_and_saveexec_b64 s[6:7], vcc
	s_cbranch_execz .LBB0_637
	s_lshl_b64 s[4:5], s[4:5], 7
	s_add_u32 s4, s8, s4
	s_waitcnt lgkmcnt(0)
	v_add_f32_e32 v12, v11, v12
	s_addc_u32 s5, s9, s5
	v_mov_b32_e32 v13, v0
	v_mov_b32_e32 v14, v0
	v_mov_b32_e32 v15, v0
	global_store_dwordx4 v0, v[12:15], s[4:5]
	s_branch .LBB0_637

.LBB0_938:
	s_ashr_i32 s6, s16, 3
	s_add_i32 s4, s6, 0x2000
	s_ashr_i32 s5, s4, 31
	s_lshl_b64 s[34:35], s[4:5], 12
	s_waitcnt lgkmcnt(0)
	v_lshl_add_u64 v[6:7], v[2:3], 0, s[34:35]
	global_load_dwordx2 v[192:193], v[6:7], off
	s_ashr_i32 s7, s6, 31
	s_lshl_b64 s[6:7], s[6:7], 10
	v_lshl_add_u64 v[22:23], v[4:5], 0, s[6:7]
	global_load_dwordx4 v[218:221], v[22:23], off
	v_add_co_u32_e64 v194, s[38:39], s22, v22
	s_nop 1
	v_addc_co_u32_e64 v195, s[38:39], 0, v23, s[38:39]
	global_load_dwordx4 v[222:225], v[194:195], off
	v_add_co_u32_e64 v194, s[38:39], s24, v22
	s_nop 1
	v_addc_co_u32_e64 v195, s[38:39], 0, v23, s[38:39]
	global_load_dwordx4 v[226:229], v[194:195], off
	v_add_co_u32_e64 v194, s[38:39], s25, v22
	s_nop 1
	v_addc_co_u32_e64 v195, s[38:39], 0, v23, s[38:39]
	global_load_dwordx4 v[230:233], v[194:195], off
	v_add_co_u32_e64 v194, s[38:39], s29, v22
	s_nop 1
	v_addc_co_u32_e64 v195, s[38:39], 0, v23, s[38:39]
	global_load_dwordx4 v[234:237], v[194:195], off
	v_add_co_u32_e64 v194, s[38:39], s14, v22
	s_nop 1
	v_addc_co_u32_e64 v195, s[38:39], 0, v23, s[38:39]
	global_load_dwordx4 v[238:241], v[194:195], off
	v_add_co_u32_e64 v194, s[38:39], s15, v22
	s_nop 1
	v_addc_co_u32_e64 v195, s[38:39], 0, v23, s[38:39]
	global_load_dwordx4 v[242:245], v[194:195], off
	v_add_co_u32_e64 v194, s[38:39], s28, v22
	s_nop 1
	v_addc_co_u32_e64 v195, s[38:39], 0, v23, s[38:39]
	global_load_dwordx4 v[188:191], v[194:195], off
	s_waitcnt vmcnt(0)
	v_lshlrev_b32_e32 v18, 16, v192
	v_and_b32_e32 v19, 0xffff0000, v192
	v_lshlrev_b32_e32 v20, 16, v193
	v_and_b32_e32 v21, 0xffff0000, v193
	v_pk_add_f32 v[18:19], v[218:219], v[18:19]
	v_pk_add_f32 v[20:21], v[220:221], v[20:21]
	v_pk_add_f32 v[18:19], v[222:223], v[18:19]
	v_pk_add_f32 v[20:21], v[224:225], v[20:21]
	v_pk_add_f32 v[18:19], v[226:227], v[18:19]
	v_pk_add_f32 v[20:21], v[228:229], v[20:21]
	v_pk_add_f32 v[18:19], v[230:231], v[18:19]
	v_pk_add_f32 v[20:21], v[232:233], v[20:21]
	v_pk_add_f32 v[18:19], v[234:235], v[18:19]
	v_pk_add_f32 v[20:21], v[236:237], v[20:21]
	v_pk_add_f32 v[18:19], v[238:239], v[18:19]
	v_pk_add_f32 v[20:21], v[240:241], v[20:21]
	v_pk_add_f32 v[18:19], v[242:243], v[18:19]
	v_pk_add_f32 v[20:21], v[244:245], v[20:21]
	v_pk_add_f32 v[16:17], v[190:191], v[20:21]
	v_pk_add_f32 v[14:15], v[188:189], v[18:19]
	v_mul_f32_e32 v18, v17, v17
	v_mul_f32_e32 v13, v15, v15
	v_fmac_f32_e32 v13, v14, v14
	v_fmac_f32_e32 v18, v16, v16
	v_add_f32_e32 v13, v13, v18
	v_bfe_u32 v18, v14, 16, 1
	v_add3_u32 v14, v14, v18, s23
	v_bfe_u32 v18, v15, 16, 1
	v_lshrrev_b32_e32 v14, 16, v14
	v_add3_u32 v15, v15, v18, s23
	v_and_or_b32 v14, v15, s83, v14
	v_bfe_u32 v15, v16, 16, 1
	v_add3_u32 v15, v16, v15, s23
	v_bfe_u32 v16, v17, 16, 1
	v_lshrrev_b32_e32 v15, 16, v15
	v_add3_u32 v16, v17, v16, s23
	v_and_or_b32 v15, v16, s83, v15
	global_store_dwordx2 v[6:7], v[14:15], off
	ds_bpermute_b32 v6, v1, v13
	s_waitcnt lgkmcnt(0)
	v_add_f32_e32 v6, v13, v6
	ds_bpermute_b32 v7, v8, v6
	s_waitcnt lgkmcnt(0)
	v_add_f32_e32 v6, v6, v7
	ds_bpermute_b32 v7, v9, v6
	s_waitcnt lgkmcnt(0)
	v_add_f32_e32 v6, v6, v7
	ds_bpermute_b32 v7, v10, v6
	s_waitcnt lgkmcnt(0)
	v_add_f32_e32 v6, v6, v7
	ds_bpermute_b32 v7, v11, v6
	s_waitcnt lgkmcnt(0)
	v_add_f32_e32 v6, v6, v7
	ds_bpermute_b32 v7, v12, v6
	s_and_saveexec_b64 s[6:7], vcc
	s_cbranch_execz .LBB0_937
	s_lshl_b64 s[4:5], s[4:5], 7
	s_add_u32 s4, s8, s4
	s_waitcnt lgkmcnt(0)
	v_add_f32_e32 v14, v6, v7
	s_addc_u32 s5, s9, s5
	v_mov_b32_e32 v15, v0
	v_mov_b32_e32 v16, v0
	v_mov_b32_e32 v17, v0
	global_store_dwordx4 v0, v[14:17], s[4:5]
	s_branch .LBB0_937

.LBB0_992:
	s_cmp_lt_i32 s78, 12
	s_cselect_b64 s[0:1], -1, 0
	s_cmp_gt_i32 s79, 11
	v_readlane_b32 s24, v254, 7
	s_cselect_b64 s[2:3], -1, 0
	s_cmpk_lt_i32 s24, 0x2000
	s_cselect_b64 s[4:5], -1, 0
	s_and_b64 s[0:1], s[0:1], s[4:5]
	s_and_b64 s[0:1], s[0:1], s[2:3]
	s_and_b64 vcc, exec, s[0:1]
	v_readlane_b32 s25, v254, 8
	s_cbranch_vccz .LBB0_999
	v_lshlrev_b32_e32 v18, 2, v202
	v_readlane_b32 s0, v252, 23
	v_mov_b32_e32 v1, 0
	v_lshlrev_b32_e32 v0, 4, v202
	v_readlane_b32 s12, v252, 35
	v_readlane_b32 s13, v252, 36
	v_or_b32_e32 v20, 0x400, v18
	v_or_b32_e32 v22, 0x500, v18
	s_waitcnt lgkmcnt(0)
	v_lshl_add_u64 v[2:3], s[12:13], 0, v[0:1]
	v_lshlrev_b32_e32 v0, 2, v20
	v_lshl_add_u64 v[4:5], s[12:13], 0, v[0:1]
	v_lshlrev_b32_e32 v0, 2, v22
	v_or_b32_e32 v24, 0x600, v18
	v_lshl_add_u64 v[6:7], s[12:13], 0, v[0:1]
	v_lshlrev_b32_e32 v0, 2, v24
	v_or_b32_e32 v26, 0x700, v18
	v_lshl_add_u64 v[8:9], s[12:13], 0, v[0:1]
	v_lshlrev_b32_e32 v0, 2, v26
	v_readlane_b32 s6, v252, 29
	v_lshl_add_u64 v[10:11], s[12:13], 0, v[0:1]
	v_lshlrev_b32_e32 v0, 3, v202
	v_lshl_add_u64 v[12:13], s[80:81], 0, v[0:1]
	v_mov_b64_e32 v[14:15], 0x2000
	v_mov_b32_e32 v0, 0x22000
	s_mov_b32 s0, 0
	v_mov_b32_e32 v16, 0x358637bd
	s_mov_b32 s6, 0x800000
	v_lshlrev_b32_e32 v17, 2, v18
	v_lshlrev_b32_e32 v18, 2, v20
	v_lshlrev_b32_e32 v19, 2, v22
	v_lshlrev_b32_e32 v20, 2, v24
	v_lshlrev_b32_e32 v21, 2, v26
	v_readlane_b32 s1, v252, 24
	v_readlane_b32 s2, v252, 25
	v_readlane_b32 s3, v252, 26
	v_readlane_b32 s4, v252, 27
	v_readlane_b32 s5, v252, 28
	v_readlane_b32 s7, v252, 30
	v_readlane_b32 s8, v252, 31
	v_readlane_b32 s9, v252, 32
	v_readlane_b32 s10, v252, 33
	v_readlane_b32 s11, v252, 34
	v_readlane_b32 s14, v252, 37
	v_readlane_b32 s15, v252, 38
	global_load_dwordx4 v[76:79], v[2:3], off
	global_load_dwordx4 v[80:83], v[2:3], off offset:1024
	global_load_dwordx4 v[84:87], v[2:3], off offset:2048
	global_load_dwordx4 v[88:91], v[2:3], off offset:3072
	global_load_dwordx4 v[92:95], v[4:5], off
	global_load_dwordx4 v[96:99], v[6:7], off
	global_load_dwordx4 v[100:103], v[8:9], off
	global_load_dwordx4 v[104:107], v[10:11], off
	s_branch .LBB0_995
.LBB0_994:
	s_lshl_b64 s[2:3], s[2:3], 12
	v_lshl_add_u64 v[28:29], v[12:13], 0, s[2:3]
	global_load_dwordx2 v[60:61], v[28:29], off
	global_load_dwordx2 v[62:63], v[28:29], off offset:512
	global_load_dwordx2 v[64:65], v[28:29], off offset:1024
	global_load_dwordx2 v[66:67], v[28:29], off offset:1536
	global_load_dwordx2 v[68:69], v[28:29], off offset:2048
	global_load_dwordx2 v[70:71], v[28:29], off offset:2560
	global_load_dwordx2 v[72:73], v[28:29], off offset:3072
	global_load_dwordx2 v[74:75], v[28:29], off offset:3584
	s_waitcnt vmcnt(0)
	v_mov_b32_e32 v30, v60
	v_mov_b32_e32 v31, v61
	v_mov_b32_e32 v24, v76
	v_mov_b32_e32 v25, v77
	v_mov_b32_e32 v26, v78
	v_mov_b32_e32 v27, v79
	v_fmamk_f32 v22, v22, 0x3a000000, v16
	v_mul_f32_e32 v23, 0x4b800000, v22
	v_cmp_gt_f32_e32 vcc, s6, v22
	v_readlane_b32 s8, v252, 23
	v_readlane_b32 s14, v252, 29
	v_cndmask_b32_e32 v22, v22, v23, vcc
	v_rsq_f32_e32 v22, v22
	v_readlane_b32 s15, v252, 30
	v_readlane_b32 s22, v252, 37
	v_readlane_b32 s23, v252, 38
	v_mul_f32_e32 v23, 0x45800000, v22
	s_lshl_b64 s[2:3], s[24:25], 13
	s_mov_b64 s[14:15], s[22:23]
	v_cndmask_b32_e32 v32, v22, v23, vcc
	s_add_u32 s2, s14, s2
	s_addc_u32 s3, s15, s3
	s_add_i32 s24, s24, s73
	s_cmpk_lt_i32 s24, 0x2000
	v_readlane_b32 s9, v252, 24
	v_readlane_b32 s10, v252, 25
	v_readlane_b32 s11, v252, 26
	v_readlane_b32 s12, v252, 27
	v_readlane_b32 s13, v252, 28
	v_readlane_b32 s16, v252, 31
	v_readlane_b32 s17, v252, 32
	v_readlane_b32 s18, v252, 33
	v_readlane_b32 s19, v252, 34
	v_readlane_b32 s20, v252, 35
	v_readlane_b32 s21, v252, 36
	v_lshlrev_b32_e32 v22, 16, v30
	v_and_b32_e32 v23, 0xffff0000, v30
	v_lshlrev_b32_e32 v30, 16, v31
	v_and_b32_e32 v31, 0xffff0000, v31
	v_pk_mul_f32 v[22:23], v[32:33], v[22:23] op_sel_hi:[0,1]
	v_pk_mul_f32 v[30:31], v[32:33], v[30:31] op_sel_hi:[0,1]
	v_pk_mul_f32 v[26:27], v[26:27], v[30:31]
	v_pk_mul_f32 v[24:25], v[24:25], v[22:23]
	global_store_dwordx4 v17, v[24:27], s[2:3] nt
	s_nop 1
	v_mov_b32_e32 v26, v62
	v_mov_b32_e32 v27, v63
	v_mov_b32_e32 v22, v80
	v_mov_b32_e32 v23, v81
	v_mov_b32_e32 v24, v82
	v_mov_b32_e32 v25, v83
	v_lshlrev_b32_e32 v30, 16, v26
	v_and_b32_e32 v31, 0xffff0000, v26
	v_lshlrev_b32_e32 v26, 16, v27
	v_and_b32_e32 v27, 0xffff0000, v27
	v_pk_mul_f32 v[30:31], v[32:33], v[30:31] op_sel_hi:[0,1]
	v_pk_mul_f32 v[26:27], v[32:33], v[26:27] op_sel_hi:[0,1]
	v_pk_mul_f32 v[24:25], v[24:25], v[26:27]
	v_pk_mul_f32 v[22:23], v[22:23], v[30:31]
	global_store_dwordx4 v17, v[22:25], s[2:3] offset:1024 nt
	s_nop 1
	v_mov_b32_e32 v26, v64
	v_mov_b32_e32 v27, v65
	v_mov_b32_e32 v22, v84
	v_mov_b32_e32 v23, v85
	v_mov_b32_e32 v24, v86
	v_mov_b32_e32 v25, v87
	v_lshlrev_b32_e32 v30, 16, v26
	v_and_b32_e32 v31, 0xffff0000, v26
	v_lshlrev_b32_e32 v26, 16, v27
	v_and_b32_e32 v27, 0xffff0000, v27
	v_pk_mul_f32 v[30:31], v[32:33], v[30:31] op_sel_hi:[0,1]
	v_pk_mul_f32 v[26:27], v[32:33], v[26:27] op_sel_hi:[0,1]
	v_pk_mul_f32 v[24:25], v[24:25], v[26:27]
	v_pk_mul_f32 v[22:23], v[22:23], v[30:31]
	global_store_dwordx4 v17, v[22:25], s[2:3] offset:2048 nt
	s_nop 1
	v_mov_b32_e32 v26, v66
	v_mov_b32_e32 v27, v67
	v_mov_b32_e32 v22, v88
	v_mov_b32_e32 v23, v89
	v_mov_b32_e32 v24, v90
	v_mov_b32_e32 v25, v91
	v_lshlrev_b32_e32 v30, 16, v26
	v_and_b32_e32 v31, 0xffff0000, v26
	v_lshlrev_b32_e32 v26, 16, v27
	v_and_b32_e32 v27, 0xffff0000, v27
	v_pk_mul_f32 v[30:31], v[32:33], v[30:31] op_sel_hi:[0,1]
	v_pk_mul_f32 v[26:27], v[32:33], v[26:27] op_sel_hi:[0,1]
	v_pk_mul_f32 v[24:25], v[24:25], v[26:27]
	v_pk_mul_f32 v[22:23], v[22:23], v[30:31]
	global_store_dwordx4 v17, v[22:25], s[2:3] offset:3072 nt
	s_nop 1
	v_mov_b32_e32 v26, v68
	v_mov_b32_e32 v27, v69
	v_mov_b32_e32 v22, v92
	v_mov_b32_e32 v23, v93
	v_mov_b32_e32 v24, v94
	v_mov_b32_e32 v25, v95
	v_lshlrev_b32_e32 v30, 16, v26
	v_and_b32_e32 v31, 0xffff0000, v26
	v_lshlrev_b32_e32 v26, 16, v27
	v_and_b32_e32 v27, 0xffff0000, v27
	v_pk_mul_f32 v[30:31], v[32:33], v[30:31] op_sel_hi:[0,1]
	v_pk_mul_f32 v[26:27], v[32:33], v[26:27] op_sel_hi:[0,1]
	v_pk_mul_f32 v[24:25], v[24:25], v[26:27]
	v_pk_mul_f32 v[22:23], v[22:23], v[30:31]
	global_store_dwordx4 v18, v[22:25], s[2:3] nt
	s_nop 1
	v_mov_b32_e32 v26, v70
	v_mov_b32_e32 v27, v71
	v_mov_b32_e32 v22, v96
	v_mov_b32_e32 v23, v97
	v_mov_b32_e32 v24, v98
	v_mov_b32_e32 v25, v99
	v_lshlrev_b32_e32 v30, 16, v26
	v_and_b32_e32 v31, 0xffff0000, v26
	v_lshlrev_b32_e32 v26, 16, v27
	v_and_b32_e32 v27, 0xffff0000, v27
	v_pk_mul_f32 v[30:31], v[32:33], v[30:31] op_sel_hi:[0,1]
	v_pk_mul_f32 v[26:27], v[32:33], v[26:27] op_sel_hi:[0,1]
	v_pk_mul_f32 v[24:25], v[24:25], v[26:27]
	v_pk_mul_f32 v[22:23], v[22:23], v[30:31]
	global_store_dwordx4 v19, v[22:25], s[2:3] nt
	s_nop 1
	v_mov_b32_e32 v26, v72
	v_mov_b32_e32 v27, v73
	v_mov_b32_e32 v22, v100
	v_mov_b32_e32 v23, v101
	v_mov_b32_e32 v24, v102
	v_mov_b32_e32 v25, v103
	v_lshlrev_b32_e32 v30, 16, v26
	v_and_b32_e32 v31, 0xffff0000, v26
	v_lshlrev_b32_e32 v26, 16, v27
	v_and_b32_e32 v27, 0xffff0000, v27
	v_pk_mul_f32 v[30:31], v[32:33], v[30:31] op_sel_hi:[0,1]
	v_pk_mul_f32 v[26:27], v[32:33], v[26:27] op_sel_hi:[0,1]
	v_pk_mul_f32 v[24:25], v[24:25], v[26:27]
	v_pk_mul_f32 v[22:23], v[22:23], v[30:31]
	global_store_dwordx4 v20, v[22:25], s[2:3] nt
	s_nop 1
	v_mov_b32_e32 v26, v74
	v_mov_b32_e32 v27, v75
	v_mov_b32_e32 v22, v104
	v_mov_b32_e32 v23, v105
	v_mov_b32_e32 v24, v106
	v_mov_b32_e32 v25, v107
	v_lshlrev_b32_e32 v28, 16, v26
	v_and_b32_e32 v29, 0xffff0000, v26
	v_lshlrev_b32_e32 v26, 16, v27
	v_and_b32_e32 v27, 0xffff0000, v27
	v_pk_mul_f32 v[28:29], v[32:33], v[28:29] op_sel_hi:[0,1]
	v_pk_mul_f32 v[26:27], v[32:33], v[26:27] op_sel_hi:[0,1]
	v_pk_mul_f32 v[24:25], v[24:25], v[26:27]
	v_pk_mul_f32 v[22:23], v[22:23], v[28:29]
	global_store_dwordx4 v21, v[22:25], s[2:3] nt
	s_cbranch_scc0 .LBB0_999
